# D1: step-1 l2norm sums reduced over a token's 8 lanes with DPP adds (quad_perm / row_half_mirror) instead of three LDS bpermute round trips (on top of C6+N3)
# baseline (speedup 1.0000x reference)
.LBB0_191:
	s_mul_hi_i32 s0, s28, 0x2aaaaaab
	s_lshr_b32 s1, s0, 31
	s_ashr_i32 s0, s0, 1
	s_add_i32 s1, s0, s1
	v_mbcnt_lo_u32_b32 v216, -1, 0
	v_mbcnt_hi_u32_b32 v216, -1, v216
	s_mul_i32 s0, s1, -12
	v_and_b32_e32 v128, 7, v216
	s_add_i32 s2, s0, s28
	v_lshlrev_b32_e32 v215, 4, v128
	v_lshl_or_b32 v48, s2, 7, v215
	v_add_u32_e32 v0, 0x600, v48
	v_add_u32_e32 v48, 0xc00, v48
	v_ashrrev_i32_e32 v1, 31, v0
	v_ashrrev_i32_e32 v49, 31, v48
	v_lshlrev_b64 v[0:1], 2, v[0:1]
	v_lshlrev_b64 v[48:49], 2, v[48:49]
	v_lshl_add_u64 v[4:5], s[34:35], 0, v[0:1]
	v_lshl_add_u64 v[6:7], s[56:57], 0, v[0:1]
	v_lshl_add_u64 v[40:41], s[50:51], 0, v[0:1]
	v_lshl_add_u64 v[52:53], s[34:35], 0, v[48:49]
	v_lshl_add_u64 v[56:57], s[56:57], 0, v[48:49]
	global_load_dwordx4 v[0:3], v[4:5], off
	global_load_dwordx4 v[12:15], v[4:5], off offset:16
	global_load_dwordx4 v[24:27], v[4:5], off offset:32
	global_load_dwordx4 v[36:39], v[4:5], off offset:48
	global_load_dwordx4 v[8:11], v[6:7], off
	global_load_dwordx4 v[20:23], v[6:7], off offset:16
	global_load_dwordx4 v[32:35], v[6:7], off offset:32
	global_load_dwordx4 v[44:47], v[6:7], off offset:48
	s_nop 0
	global_load_dwordx4 v[4:7], v[40:41], off
	global_load_dwordx4 v[16:19], v[40:41], off offset:16
	global_load_dwordx4 v[28:31], v[40:41], off offset:32
	s_nop 0
	global_load_dwordx4 v[40:43], v[40:41], off offset:48
	v_lshl_add_u64 v[210:211], s[50:51], 0, v[48:49]
	global_load_dwordx4 v[48:51], v[52:53], off offset:48
	global_load_dwordx4 v[60:63], v[52:53], off offset:32
	global_load_dwordx4 v[194:197], v[52:53], off offset:16
	global_load_dwordx4 v[206:209], v[52:53], off
	s_nop 0
	global_load_dwordx4 v[52:55], v[56:57], off offset:48
	global_load_dwordx4 v[186:189], v[56:57], off offset:32
	global_load_dwordx4 v[198:201], v[56:57], off offset:16
	global_load_dwordx4 v[218:221], v[56:57], off
	s_nop 0
	global_load_dwordx4 v[56:59], v[210:211], off offset:48
	global_load_dwordx4 v[190:193], v[210:211], off offset:32
	global_load_dwordx4 v[202:205], v[210:211], off offset:16
	global_load_dwordx4 v[222:225], v[210:211], off
	s_waitcnt vmcnt(0)
	v_lshlrev_b32_e32 v212, 16, v178
	v_and_b32_e32 v213, 0xffff0000, v178
	v_lshlrev_b32_e32 v210, 16, v182
	v_and_b32_e32 v211, 0xffff0000, v182
	v_lshlrev_b32_e32 v178, 16, v179
	v_and_b32_e32 v179, 0xffff0000, v179
	v_lshlrev_b32_e32 v182, 16, v183
	v_and_b32_e32 v183, 0xffff0000, v183
	v_and_b32_e32 v214, 63, v216
	s_mov_b32 s0, 0x358637bd
	v_pk_mul_f32 v[212:213], v[218:219], v[212:213]
	s_nop 0
	v_pk_fma_f32 v[206:207], v[206:207], v[210:211], v[212:213]
	v_lshlrev_b32_e32 v210, 16, v174
	v_and_b32_e32 v211, 0xffff0000, v174
	v_pk_fma_f32 v[206:207], v[222:223], v[210:211], v[206:207]
	v_pk_mul_f32 v[178:179], v[220:221], v[178:179]
	v_mul_f32_e32 v174, 0xbfb8aa3b, v206
	v_exp_f32_e32 v174, v174
	v_pk_fma_f32 v[178:179], v[208:209], v[182:183], v[178:179]
	v_lshlrev_b32_e32 v182, 16, v180
	v_and_b32_e32 v183, 0xffff0000, v180
	v_add_f32_e32 v174, 1.0, v174
	v_rcp_f32_e32 v210, v174
	v_mul_f32_e32 v174, 0xbfb8aa3b, v207
	v_exp_f32_e32 v174, v174
	v_pk_mul_f32 v[182:183], v[198:199], v[182:183]
	v_lshlrev_b32_e32 v180, 16, v181
	v_and_b32_e32 v181, 0xffff0000, v181
	v_add_f32_e32 v174, 1.0, v174
	v_rcp_f32_e32 v211, v174
	v_lshlrev_b32_e32 v174, 16, v175
	v_and_b32_e32 v175, 0xffff0000, v175
	v_pk_fma_f32 v[174:175], v[224:225], v[174:175], v[178:179]
	v_pk_mul_f32 v[180:181], v[200:201], v[180:181]
	v_mul_f32_e32 v178, 0xbfb8aa3b, v174
	v_mul_f32_e32 v179, 0xbfb8aa3b, v175
	v_exp_f32_e32 v178, v178
	v_exp_f32_e32 v179, v179
	v_pk_mul_f32 v[212:213], v[206:207], v[210:211]
	v_add_f32_e32 v178, 1.0, v178
	v_add_f32_e32 v179, 1.0, v179
	v_rcp_f32_e32 v178, v178
	v_rcp_f32_e32 v179, v179
	s_nop 0
	v_pk_mul_f32 v[174:175], v[174:175], v[178:179]
	v_lshlrev_b32_e32 v178, 16, v184
	v_and_b32_e32 v179, 0xffff0000, v184
	v_pk_fma_f32 v[178:179], v[194:195], v[178:179], v[182:183]
	v_lshlrev_b32_e32 v182, 16, v176
	v_and_b32_e32 v183, 0xffff0000, v176
	v_pk_fma_f32 v[178:179], v[202:203], v[182:183], v[178:179]
	s_nop 0
	v_mul_f32_e32 v176, 0xbfb8aa3b, v178
	v_exp_f32_e32 v176, v176
	s_nop 0
	v_add_f32_e32 v176, 1.0, v176
	v_rcp_f32_e32 v182, v176
	v_mul_f32_e32 v176, 0xbfb8aa3b, v179
	v_exp_f32_e32 v176, v176
	s_nop 0
	v_add_f32_e32 v176, 1.0, v176
	v_rcp_f32_e32 v183, v176
	v_lshlrev_b32_e32 v176, 16, v177
	v_and_b32_e32 v177, 0xffff0000, v177
	v_pk_mul_f32 v[178:179], v[178:179], v[182:183]
	v_lshlrev_b32_e32 v182, 16, v185
	v_and_b32_e32 v183, 0xffff0000, v185
	v_pk_fma_f32 v[180:181], v[196:197], v[182:183], v[180:181]
	v_lshlrev_b32_e32 v182, 16, v124
	v_pk_fma_f32 v[176:177], v[204:205], v[176:177], v[180:181]
	v_and_b32_e32 v183, 0xffff0000, v124
	v_mul_f32_e32 v180, 0xbfb8aa3b, v176
	v_mul_f32_e32 v181, 0xbfb8aa3b, v177
	v_exp_f32_e32 v180, v180
	v_exp_f32_e32 v181, v181
	v_pk_mul_f32 v[182:183], v[186:187], v[182:183]
	v_add_u32_e32 v186, s87, v216
	v_add_f32_e32 v180, 1.0, v180
	v_add_f32_e32 v181, 1.0, v181
	v_rcp_f32_e32 v180, v180
	v_rcp_f32_e32 v181, v181
	v_ashrrev_i32_e32 v187, 3, v186
	v_pk_mul_f32 v[176:177], v[176:177], v[180:181]
	v_lshlrev_b32_e32 v180, 16, v134
	v_and_b32_e32 v181, 0xffff0000, v134
	v_pk_fma_f32 v[60:61], v[60:61], v[180:181], v[182:183]
	v_lshlrev_b32_e32 v180, 16, v146
	v_and_b32_e32 v181, 0xffff0000, v146
	v_pk_fma_f32 v[60:61], v[190:191], v[180:181], v[60:61]
	v_lshlrev_b32_e32 v134, 16, v135
	v_mul_f32_e32 v124, 0xbfb8aa3b, v60
	v_exp_f32_e32 v124, v124
	v_and_b32_e32 v135, 0xffff0000, v135
	v_add_f32_e32 v124, 1.0, v124
	v_rcp_f32_e32 v180, v124
	v_mul_f32_e32 v124, 0xbfb8aa3b, v61
	v_exp_f32_e32 v124, v124
	s_nop 0
	v_add_f32_e32 v124, 1.0, v124
	v_rcp_f32_e32 v181, v124
	v_lshlrev_b32_e32 v124, 16, v125
	v_and_b32_e32 v125, 0xffff0000, v125
	v_pk_mul_f32 v[124:125], v[188:189], v[124:125]
	v_pk_mul_f32 v[60:61], v[60:61], v[180:181]
	v_pk_fma_f32 v[62:63], v[62:63], v[134:135], v[124:125]
	v_lshlrev_b32_e32 v124, 16, v147
	v_and_b32_e32 v125, 0xffff0000, v147
	v_pk_fma_f32 v[62:63], v[192:193], v[124:125], v[62:63]
	v_lshlrev_b32_e32 v134, 16, v126
	v_mul_f32_e32 v124, 0xbfb8aa3b, v62
	v_mul_f32_e32 v125, 0xbfb8aa3b, v63
	v_exp_f32_e32 v124, v124
	v_exp_f32_e32 v125, v125
	v_and_b32_e32 v135, 0xffff0000, v126
	v_pk_mul_f32 v[52:53], v[52:53], v[134:135]
	v_add_f32_e32 v124, 1.0, v124
	v_add_f32_e32 v125, 1.0, v125
	v_rcp_f32_e32 v124, v124
	v_rcp_f32_e32 v125, v125
	s_nop 0
	v_pk_mul_f32 v[62:63], v[62:63], v[124:125]
	v_lshlrev_b32_e32 v124, 16, v136
	v_and_b32_e32 v125, 0xffff0000, v136
	v_pk_fma_f32 v[48:49], v[48:49], v[124:125], v[52:53]
	v_lshlrev_b32_e32 v52, 16, v148
	v_and_b32_e32 v53, 0xffff0000, v148
	v_pk_fma_f32 v[48:49], v[56:57], v[52:53], v[48:49]
	v_lshlrev_b32_e32 v56, 16, v127
	v_mul_f32_e32 v52, 0xbfb8aa3b, v48
	v_mul_f32_e32 v53, 0xbfb8aa3b, v49
	v_exp_f32_e32 v52, v52
	v_exp_f32_e32 v53, v53
	v_and_b32_e32 v57, 0xffff0000, v127
	v_pk_mul_f32 v[54:55], v[54:55], v[56:57]
	v_add_f32_e32 v52, 1.0, v52
	v_add_f32_e32 v53, 1.0, v53
	v_rcp_f32_e32 v52, v52
	v_rcp_f32_e32 v53, v53
	v_lshlrev_b32_e32 v124, 2, v214
	v_pk_mul_f32 v[48:49], v[48:49], v[52:53]
	v_lshlrev_b32_e32 v52, 16, v137
	v_and_b32_e32 v53, 0xffff0000, v137
	v_pk_fma_f32 v[50:51], v[50:51], v[52:53], v[54:55]
	v_lshlrev_b32_e32 v52, 16, v149
	v_and_b32_e32 v53, 0xffff0000, v149
	v_pk_fma_f32 v[50:51], v[58:59], v[52:53], v[50:51]
	v_lshlrev_b32_e32 v54, 16, v99
	v_mul_f32_e32 v52, 0xbfb8aa3b, v50
	v_mul_f32_e32 v53, 0xbfb8aa3b, v51
	v_exp_f32_e32 v52, v52
	v_exp_f32_e32 v53, v53
	v_and_b32_e32 v55, 0xffff0000, v99
	v_pk_mul_f32 v[54:55], v[168:169], v[54:55]
	v_add_f32_e32 v52, 1.0, v52
	v_add_f32_e32 v53, 1.0, v53
	v_rcp_f32_e32 v52, v52
	v_rcp_f32_e32 v53, v53
	v_lshlrev_b32_e32 v58, 16, v98
	v_and_b32_e32 v59, 0xffff0000, v98
	v_pk_mul_f32 v[58:59], v[166:167], v[58:59]
	v_pk_mul_f32 v[50:51], v[50:51], v[52:53]
	v_lshlrev_b32_e32 v52, 16, v107
	v_and_b32_e32 v53, 0xffff0000, v107
	v_pk_fma_f32 v[52:53], v[164:165], v[52:53], v[54:55]
	v_lshlrev_b32_e32 v54, 16, v111
	v_and_b32_e32 v55, 0xffff0000, v111
	v_pk_fma_f32 v[52:53], v[172:173], v[54:55], v[52:53]
	v_and_b32_e32 v107, 0xffff0000, v97
	v_mul_f32_e32 v54, 0xbfb8aa3b, v52
	v_mul_f32_e32 v55, 0xbfb8aa3b, v53
	v_exp_f32_e32 v54, v54
	v_exp_f32_e32 v55, v55
	v_and_b32_e32 v111, 0xffff0000, v104
	v_add_f32_e32 v54, 1.0, v54
	v_add_f32_e32 v55, 1.0, v55
	v_rcp_f32_e32 v54, v54
	v_rcp_f32_e32 v55, v55
	s_nop 0
	v_pk_mul_f32 v[52:53], v[52:53], v[54:55]
	v_lshlrev_b32_e32 v54, 16, v106
	v_and_b32_e32 v55, 0xffff0000, v106
	v_pk_fma_f32 v[54:55], v[162:163], v[54:55], v[58:59]
	v_lshlrev_b32_e32 v58, 16, v110
	v_and_b32_e32 v59, 0xffff0000, v110
	v_pk_fma_f32 v[54:55], v[170:171], v[58:59], v[54:55]
	v_lshlrev_b32_e32 v106, 16, v97
	v_mul_f32_e32 v58, 0xbfb8aa3b, v54
	v_mul_f32_e32 v59, 0xbfb8aa3b, v55
	v_exp_f32_e32 v58, v58
	v_exp_f32_e32 v59, v59
	v_pk_mul_f32 v[106:107], v[156:157], v[106:107]
	v_lshlrev_b32_e32 v110, 16, v104
	v_add_f32_e32 v58, 1.0, v58
	v_add_f32_e32 v59, 1.0, v59
	v_rcp_f32_e32 v58, v58
	v_rcp_f32_e32 v59, v59
	v_lshlrev_b32_e32 v104, 16, v96
	v_pk_mul_f32 v[56:57], v[52:53], v[52:53]
	v_pk_mul_f32 v[54:55], v[54:55], v[58:59]
	v_lshlrev_b32_e32 v58, 16, v105
	v_and_b32_e32 v59, 0xffff0000, v105
	v_pk_fma_f32 v[58:59], v[152:153], v[58:59], v[106:107]
	v_lshlrev_b32_e32 v106, 16, v109
	v_and_b32_e32 v107, 0xffff0000, v109
	v_pk_fma_f32 v[58:59], v[160:161], v[106:107], v[58:59]
	v_and_b32_e32 v105, 0xffff0000, v96
	v_mul_f32_e32 v97, 0xbfb8aa3b, v58
	v_exp_f32_e32 v97, v97
	v_pk_mul_f32 v[98:99], v[54:55], v[54:55]
	v_add_f32_e32 v97, 1.0, v97
	v_rcp_f32_e32 v106, v97
	v_mul_f32_e32 v97, 0xbfb8aa3b, v59
	v_exp_f32_e32 v97, v97
	s_nop 0
	v_add_f32_e32 v97, 1.0, v97
	v_rcp_f32_e32 v107, v97
	v_pk_mul_f32 v[96:97], v[154:155], v[104:105]
	v_lshlrev_b32_e32 v104, 16, v108
	v_pk_fma_f32 v[96:97], v[150:151], v[110:111], v[96:97]
	v_and_b32_e32 v105, 0xffff0000, v108
	v_pk_fma_f32 v[96:97], v[158:159], v[104:105], v[96:97]
	v_lshlrev_b32_e32 v110, 16, v75
	v_mul_f32_e32 v104, 0xbfb8aa3b, v96
	v_mul_f32_e32 v105, 0xbfb8aa3b, v97
	v_exp_f32_e32 v104, v104
	v_exp_f32_e32 v105, v105
	v_and_b32_e32 v111, 0xffff0000, v75
	v_pk_mul_f32 v[110:111], v[140:141], v[110:111]
	v_add_f32_e32 v104, 1.0, v104
	v_add_f32_e32 v105, 1.0, v105
	v_rcp_f32_e32 v104, v104
	v_rcp_f32_e32 v105, v105
	v_pk_mul_f32 v[58:59], v[58:59], v[106:107]
	v_pk_mul_f32 v[96:97], v[96:97], v[104:105]
	v_lshlrev_b32_e32 v104, 16, v91
	v_and_b32_e32 v105, 0xffff0000, v91
	v_pk_fma_f32 v[104:105], v[132:133], v[104:105], v[110:111]
	v_lshlrev_b32_e32 v110, 16, v87
	v_and_b32_e32 v111, 0xffff0000, v87
	v_pk_fma_f32 v[104:105], v[144:145], v[110:111], v[104:105]
	v_and_b32_e32 v91, 0xffff0000, v74
	v_mul_f32_e32 v75, 0xbfb8aa3b, v104
	v_exp_f32_e32 v75, v75
	v_pk_mul_f32 v[108:109], v[96:97], v[96:97]
	v_pk_mul_f32 v[106:107], v[58:59], v[58:59]
	v_add_f32_e32 v75, 1.0, v75
	v_rcp_f32_e32 v110, v75
	v_mul_f32_e32 v75, 0xbfb8aa3b, v105
	v_exp_f32_e32 v75, v75
	s_nop 0
	v_add_f32_e32 v75, 1.0, v75
	v_rcp_f32_e32 v111, v75
	s_nop 0
	v_pk_mul_f32 v[104:105], v[104:105], v[110:111]
	v_lshlrev_b32_e32 v110, 16, v90
	v_and_b32_e32 v111, 0xffff0000, v90
	v_lshlrev_b32_e32 v90, 16, v74
	v_pk_mul_f32 v[74:75], v[138:139], v[90:91]
	v_lshlrev_b32_e32 v90, 16, v86
	v_pk_fma_f32 v[74:75], v[130:131], v[110:111], v[74:75]
	v_and_b32_e32 v91, 0xffff0000, v86
	v_pk_fma_f32 v[74:75], v[142:143], v[90:91], v[74:75]
	v_lshlrev_b32_e32 v90, 16, v73
	v_mul_f32_e32 v86, 0xbfb8aa3b, v74
	v_mul_f32_e32 v87, 0xbfb8aa3b, v75
	v_exp_f32_e32 v86, v86
	v_exp_f32_e32 v87, v87
	v_and_b32_e32 v91, 0xffff0000, v73
	v_pk_mul_f32 v[90:91], v[118:119], v[90:91]
	v_add_f32_e32 v86, 1.0, v86
	v_add_f32_e32 v87, 1.0, v87
	v_rcp_f32_e32 v86, v86
	v_rcp_f32_e32 v87, v87
	s_nop 0
	v_pk_mul_f32 v[74:75], v[74:75], v[86:87]
	v_lshlrev_b32_e32 v86, 16, v89
	v_and_b32_e32 v87, 0xffff0000, v89
	v_pk_fma_f32 v[86:87], v[114:115], v[86:87], v[90:91]
	v_lshlrev_b32_e32 v90, 16, v85
	v_and_b32_e32 v91, 0xffff0000, v85
	v_pk_fma_f32 v[86:87], v[122:123], v[90:91], v[86:87]
	v_and_b32_e32 v89, 0xffff0000, v72
	v_mul_f32_e32 v73, 0xbfb8aa3b, v86
	v_exp_f32_e32 v73, v73
	s_nop 0
	v_add_f32_e32 v73, 1.0, v73
	v_rcp_f32_e32 v90, v73
	v_mul_f32_e32 v73, 0xbfb8aa3b, v87
	v_exp_f32_e32 v73, v73
	s_nop 0
	v_add_f32_e32 v73, 1.0, v73
	v_rcp_f32_e32 v91, v73
	s_nop 0
	v_pk_mul_f32 v[86:87], v[86:87], v[90:91]
	v_lshlrev_b32_e32 v90, 16, v88
	v_and_b32_e32 v91, 0xffff0000, v88
	v_lshlrev_b32_e32 v88, 16, v72
	v_pk_mul_f32 v[72:73], v[116:117], v[88:89]
	v_lshlrev_b32_e32 v88, 16, v84
	v_pk_fma_f32 v[72:73], v[112:113], v[90:91], v[72:73]
	v_and_b32_e32 v89, 0xffff0000, v84
	v_pk_fma_f32 v[72:73], v[120:121], v[88:89], v[72:73]
	v_lshlrev_b32_e32 v88, 16, v83
	v_mul_f32_e32 v84, 0xbfb8aa3b, v72
	v_mul_f32_e32 v85, 0xbfb8aa3b, v73
	v_exp_f32_e32 v84, v84
	v_exp_f32_e32 v85, v85
	v_and_b32_e32 v89, 0xffff0000, v83
	v_pk_mul_f32 v[46:47], v[46:47], v[88:89]
	v_add_f32_e32 v84, 1.0, v84
	v_add_f32_e32 v85, 1.0, v85
	v_rcp_f32_e32 v84, v84
	v_rcp_f32_e32 v85, v85
	s_nop 0
	v_pk_mul_f32 v[72:73], v[72:73], v[84:85]
	v_lshlrev_b32_e32 v84, 16, v95
	v_and_b32_e32 v85, 0xffff0000, v95
	v_pk_fma_f32 v[38:39], v[38:39], v[84:85], v[46:47]
	v_lshlrev_b32_e32 v46, 16, v103
	v_and_b32_e32 v47, 0xffff0000, v103
	v_lshlrev_b32_e32 v84, 16, v82
	v_and_b32_e32 v85, 0xffff0000, v82
	v_pk_fma_f32 v[38:39], v[42:43], v[46:47], v[38:39]
	v_lshlrev_b32_e32 v46, 16, v94
	v_and_b32_e32 v47, 0xffff0000, v94
	v_pk_mul_f32 v[44:45], v[44:45], v[84:85]
	v_mul_f32_e32 v42, 0xbfb8aa3b, v38
	v_pk_fma_f32 v[36:37], v[36:37], v[46:47], v[44:45]
	v_lshlrev_b32_e32 v44, 16, v102
	v_and_b32_e32 v45, 0xffff0000, v102
	v_lshlrev_b32_e32 v46, 16, v81
	v_and_b32_e32 v47, 0xffff0000, v81
	v_pk_fma_f32 v[36:37], v[40:41], v[44:45], v[36:37]
	v_lshlrev_b32_e32 v44, 16, v93
	v_and_b32_e32 v45, 0xffff0000, v93
	v_pk_mul_f32 v[34:35], v[34:35], v[46:47]
	v_mul_f32_e32 v40, 0xbfb8aa3b, v36
	v_pk_fma_f32 v[26:27], v[26:27], v[44:45], v[34:35]
	v_lshlrev_b32_e32 v34, 16, v101
	v_and_b32_e32 v35, 0xffff0000, v101
	v_lshlrev_b32_e32 v44, 16, v80
	v_and_b32_e32 v45, 0xffff0000, v80
	v_pk_fma_f32 v[26:27], v[30:31], v[34:35], v[26:27]
	v_lshlrev_b32_e32 v34, 16, v92
	v_and_b32_e32 v35, 0xffff0000, v92
	v_pk_mul_f32 v[32:33], v[32:33], v[44:45]
	v_mul_f32_e32 v30, 0xbfb8aa3b, v26
	v_pk_fma_f32 v[24:25], v[24:25], v[34:35], v[32:33]
	v_lshlrev_b32_e32 v32, 16, v100
	v_and_b32_e32 v33, 0xffff0000, v100
	v_lshlrev_b32_e32 v34, 16, v67
	v_and_b32_e32 v35, 0xffff0000, v67
	v_pk_fma_f32 v[24:25], v[28:29], v[32:33], v[24:25]
	v_lshlrev_b32_e32 v32, 16, v71
	v_and_b32_e32 v33, 0xffff0000, v71
	v_pk_mul_f32 v[22:23], v[22:23], v[34:35]
	v_mul_f32_e32 v28, 0xbfb8aa3b, v24
	v_pk_fma_f32 v[14:15], v[14:15], v[32:33], v[22:23]
	v_lshlrev_b32_e32 v22, 16, v79
	v_and_b32_e32 v23, 0xffff0000, v79
	v_pk_fma_f32 v[14:15], v[18:19], v[22:23], v[14:15]
	v_lshlrev_b32_e32 v22, 16, v66
	v_mul_f32_e32 v18, 0xbfb8aa3b, v14
	v_mul_f32_e32 v19, 0xbfb8aa3b, v15
	v_exp_f32_e32 v18, v18
	v_exp_f32_e32 v19, v19
	v_and_b32_e32 v23, 0xffff0000, v66
	v_pk_mul_f32 v[20:21], v[20:21], v[22:23]
	v_add_f32_e32 v18, 1.0, v18
	v_add_f32_e32 v19, 1.0, v19
	v_rcp_f32_e32 v18, v18
	v_rcp_f32_e32 v19, v19
	v_mul_f32_e32 v29, 0xbfb8aa3b, v25
	v_exp_f32_e32 v28, v28
	v_exp_f32_e32 v29, v29
	v_pk_mul_f32 v[14:15], v[14:15], v[18:19]
	v_lshlrev_b32_e32 v18, 16, v70
	v_and_b32_e32 v19, 0xffff0000, v70
	v_pk_fma_f32 v[12:13], v[12:13], v[18:19], v[20:21]
	v_lshlrev_b32_e32 v18, 16, v78
	v_and_b32_e32 v19, 0xffff0000, v78
	v_pk_fma_f32 v[12:13], v[16:17], v[18:19], v[12:13]
	v_lshlrev_b32_e32 v18, 16, v65
	v_mul_f32_e32 v16, 0xbfb8aa3b, v12
	v_mul_f32_e32 v17, 0xbfb8aa3b, v13
	v_exp_f32_e32 v16, v16
	v_exp_f32_e32 v17, v17
	v_and_b32_e32 v19, 0xffff0000, v65
	v_pk_mul_f32 v[10:11], v[10:11], v[18:19]
	v_add_f32_e32 v16, 1.0, v16
	v_add_f32_e32 v17, 1.0, v17
	v_rcp_f32_e32 v16, v16
	v_rcp_f32_e32 v17, v17
	v_mul_f32_e32 v31, 0xbfb8aa3b, v27
	v_exp_f32_e32 v30, v30
	v_exp_f32_e32 v31, v31
	v_pk_mul_f32 v[12:13], v[12:13], v[16:17]
	v_lshlrev_b32_e32 v16, 16, v69
	v_and_b32_e32 v17, 0xffff0000, v69
	v_pk_fma_f32 v[2:3], v[2:3], v[16:17], v[10:11]
	v_lshlrev_b32_e32 v10, 16, v77
	v_and_b32_e32 v11, 0xffff0000, v77
	v_pk_fma_f32 v[2:3], v[6:7], v[10:11], v[2:3]
	v_lshlrev_b32_e32 v10, 16, v64
	v_mul_f32_e32 v6, 0xbfb8aa3b, v2
	v_mul_f32_e32 v7, 0xbfb8aa3b, v3
	v_exp_f32_e32 v6, v6
	v_exp_f32_e32 v7, v7
	v_and_b32_e32 v11, 0xffff0000, v64
	v_pk_mul_f32 v[8:9], v[8:9], v[10:11]
	v_add_f32_e32 v6, 1.0, v6
	v_add_f32_e32 v7, 1.0, v7
	v_rcp_f32_e32 v6, v6
	v_rcp_f32_e32 v7, v7
	v_mul_f32_e32 v41, 0xbfb8aa3b, v37
	v_mov_b32_e32 v23, v73
	v_exp_f32_e32 v40, v40
	v_pk_mul_f32 v[2:3], v[2:3], v[6:7]
	v_lshlrev_b32_e32 v6, 16, v68
	v_and_b32_e32 v7, 0xffff0000, v68
	v_pk_fma_f32 v[0:1], v[0:1], v[6:7], v[8:9]
	v_lshlrev_b32_e32 v6, 16, v76
	v_and_b32_e32 v7, 0xffff0000, v76
	v_pk_fma_f32 v[0:1], v[4:5], v[6:7], v[0:1]
	v_exp_f32_e32 v41, v41
	v_mul_f32_e32 v4, 0xbfb8aa3b, v0
	v_mul_f32_e32 v5, 0xbfb8aa3b, v1
	v_exp_f32_e32 v4, v4
	v_exp_f32_e32 v5, v5
	v_add_f32_e32 v28, 1.0, v28
	v_add_f32_e32 v29, 1.0, v29
	v_add_f32_e32 v4, 1.0, v4
	v_add_f32_e32 v5, 1.0, v5
	v_rcp_f32_e32 v4, v4
	v_rcp_f32_e32 v5, v5
	v_mov_b32_e32 v21, v72
	v_mul_f32_e32 v43, 0xbfb8aa3b, v39
	v_rcp_f32_e32 v28, v28
	v_pk_mul_f32 v[0:1], v[0:1], v[4:5]
	v_rcp_f32_e32 v29, v29
	v_mov_b32_e32 v22, v1
	v_mov_b32_e32 v20, v0
	v_pk_mul_f32 v[22:23], v[22:23], v[22:23]
	v_mov_b32_e32 v16, v2
	v_mov_b32_e32 v17, v86
	v_pk_fma_f32 v[20:21], v[20:21], v[20:21], v[22:23]
	v_exp_f32_e32 v42, v42
	v_exp_f32_e32 v43, v43
	v_add_f32_e32 v30, 1.0, v30
	v_add_f32_e32 v31, 1.0, v31
	v_mov_b32_e32 v18, v3
	v_mov_b32_e32 v19, v87
	v_pk_fma_f32 v[16:17], v[16:17], v[16:17], v[20:21]
	v_rcp_f32_e32 v30, v30
	v_rcp_f32_e32 v31, v31
	v_mov_b32_e32 v8, v12
	v_mov_b32_e32 v9, v74
	v_pk_fma_f32 v[16:17], v[18:19], v[18:19], v[16:17]
	v_add_f32_e32 v40, 1.0, v40
	v_add_f32_e32 v41, 1.0, v41
	v_mov_b32_e32 v10, v13
	v_mov_b32_e32 v11, v75
	v_pk_fma_f32 v[8:9], v[8:9], v[8:9], v[16:17]
	v_rcp_f32_e32 v40, v40
	v_rcp_f32_e32 v41, v41
	v_pk_mul_f32 v[24:25], v[24:25], v[28:29]
	v_mov_b32_e32 v4, v14
	v_mov_b32_e32 v5, v104
	v_pk_fma_f32 v[8:9], v[10:11], v[10:11], v[8:9]
	v_add_f32_e32 v42, 1.0, v42
	v_add_f32_e32 v43, 1.0, v43
	v_pk_mul_f32 v[28:29], v[24:25], v[24:25]
	v_mov_b32_e32 v6, v15
	v_mov_b32_e32 v7, v105
	v_pk_fma_f32 v[4:5], v[4:5], v[4:5], v[8:9]
	v_rcp_f32_e32 v42, v42
	v_rcp_f32_e32 v43, v43
	v_pk_mul_f32 v[26:27], v[26:27], v[30:31]
	v_pk_fma_f32 v[4:5], v[6:7], v[6:7], v[4:5]
	v_mov_b32_e32 v6, v28
	v_mov_b32_e32 v7, v108
	v_pk_mul_f32 v[30:31], v[26:27], v[26:27]
	v_pk_add_f32 v[4:5], v[6:7], v[4:5]
	v_mov_b32_e32 v108, v29
	v_pk_mul_f32 v[36:37], v[36:37], v[40:41]
	v_pk_add_f32 v[4:5], v[108:109], v[4:5]
	v_mov_b32_e32 v6, v30
	v_mov_b32_e32 v7, v106
	v_pk_mul_f32 v[40:41], v[36:37], v[36:37]
	v_pk_add_f32 v[4:5], v[6:7], v[4:5]
	v_mov_b32_e32 v106, v31
	v_pk_mul_f32 v[38:39], v[38:39], v[42:43]
	v_pk_add_f32 v[4:5], v[106:107], v[4:5]
	v_mov_b32_e32 v6, v40
	v_mov_b32_e32 v7, v98
	v_pk_mul_f32 v[42:43], v[38:39], v[38:39]
	v_pk_add_f32 v[4:5], v[6:7], v[4:5]
	v_mov_b32_e32 v98, v41
	v_pk_add_f32 v[4:5], v[98:99], v[4:5]
	v_mov_b32_e32 v6, v42
	v_mov_b32_e32 v7, v56
	v_pk_add_f32 v[4:5], v[6:7], v[4:5]
	v_mov_b32_e32 v56, v43
	v_pk_add_f32 v[4:5], v[56:57], v[4:5]
	s_nop 1
	v_add_f32_dpp v4, v4, v4 quad_perm:[1,0,3,2] row_mask:0xf bank_mask:0xf
	v_add_f32_dpp v5, v5, v5 quad_perm:[1,0,3,2] row_mask:0xf bank_mask:0xf
	s_nop 0
	v_add_f32_dpp v4, v4, v4 quad_perm:[2,3,0,1] row_mask:0xf bank_mask:0xf
	v_add_f32_dpp v5, v5, v5 quad_perm:[2,3,0,1] row_mask:0xf bank_mask:0xf
	s_nop 0
	v_add_f32_dpp v4, v4, v4 row_half_mirror row_mask:0xf bank_mask:0xf
	v_add_f32_dpp v5, v5, v5 row_half_mirror row_mask:0xf bank_mask:0xf
	s_nop 0
	v_pk_add_f32 v[16:17], v[4:5], s[0:1] op_sel_hi:[1,0]
	s_movk_i32 s0, 0x70
	v_mul_f32_e32 v4, 0x4b800000, v17
	v_cmp_gt_f32_e64 s[38:39], s25, v17
	v_cmp_gt_f32_e32 vcc, s25, v16
	s_nop 0
	v_cndmask_b32_e64 v4, v17, v4, s[38:39]
	v_mul_f32_e32 v17, 0x4b800000, v16
	v_cndmask_b32_e32 v16, v16, v17, vcc
	v_rsq_f32_e32 v16, v16
	v_rsq_f32_e32 v4, v4
	v_mul_f32_e32 v17, 0x45800000, v16
	v_mul_f32_e32 v5, 0x45800000, v4
	v_cndmask_b32_e32 v16, v16, v17, vcc
	v_cndmask_b32_e64 v4, v4, v5, s[38:39]
	v_pk_mul_f32 v[0:1], v[0:1], v[16:17] op_sel_hi:[1,0]
	v_pk_mul_f32 v[2:3], v[2:3], v[16:17] op_sel_hi:[1,0]
	v_mul_f32_e32 v18, 0x3db504f3, v4
	v_cvt_pk_bf16_f32 v0, v0, v1
	v_cvt_pk_bf16_f32 v1, v2, v3
	v_pk_mul_f32 v[2:3], v[12:13], v[16:17] op_sel_hi:[1,0]
	v_pk_mul_f32 v[12:13], v[14:15], v[16:17] op_sel_hi:[1,0]
	v_pk_mul_f32 v[4:5], v[72:73], v[18:19] op_sel_hi:[1,0]
	v_pk_mul_f32 v[6:7], v[86:87], v[18:19] op_sel_hi:[1,0]
	v_cvt_pk_bf16_f32 v2, v2, v3
	v_cvt_pk_bf16_f32 v3, v12, v13
	v_pk_mul_f32 v[12:13], v[24:25], v[16:17] op_sel_hi:[1,0]
	v_pk_mul_f32 v[14:15], v[26:27], v[16:17] op_sel_hi:[1,0]
	v_cvt_pk_bf16_f32 v4, v4, v5
	v_cvt_pk_bf16_f32 v5, v6, v7
	v_pk_mul_f32 v[6:7], v[74:75], v[18:19] op_sel_hi:[1,0]
	v_pk_mul_f32 v[8:9], v[104:105], v[18:19] op_sel_hi:[1,0]
	v_cvt_pk_bf16_f32 v12, v12, v13
	v_cvt_pk_bf16_f32 v13, v14, v15
	v_pk_mul_f32 v[14:15], v[36:37], v[16:17] op_sel_hi:[1,0]
	v_pk_mul_f32 v[16:17], v[38:39], v[16:17] op_sel_hi:[1,0]
	v_cvt_pk_bf16_f32 v6, v6, v7
	v_cvt_pk_bf16_f32 v7, v8, v9
	v_pk_mul_f32 v[8:9], v[96:97], v[18:19] op_sel_hi:[1,0]
	v_pk_mul_f32 v[10:11], v[58:59], v[18:19] op_sel_hi:[1,0]
	v_cvt_pk_bf16_f32 v14, v14, v15
	v_cvt_pk_bf16_f32 v15, v16, v17
	v_mul_lo_u32 v16, v187, s96
	v_lshlrev_b32_e32 v17, 5, v128
	v_cvt_pk_bf16_f32 v8, v8, v9
	v_cvt_pk_bf16_f32 v9, v10, v11
	v_pk_mul_f32 v[10:11], v[54:55], v[18:19] op_sel_hi:[1,0]
	v_pk_mul_f32 v[18:19], v[52:53], v[18:19] op_sel_hi:[1,0]
	v_add3_u32 v16, 0, v16, v17
	v_cvt_pk_bf16_f32 v10, v10, v11
	v_cvt_pk_bf16_f32 v11, v18, v19
	ds_write_b128 v16, v[4:7] offset:17408
	ds_write_b128 v16, v[8:11] offset:17424
	ds_write_b128 v16, v[0:3]
	ds_write_b128 v16, v[12:15] offset:16
	v_lshrrev_b32_e32 v4, 6, v186
	v_xor_b32_e32 v4, v4, v216
	v_lshlrev_b32_e32 v5, 1, v187
	v_lshlrev_b32_e32 v4, 4, v4
	v_and_b32_e32 v5, 14, v5
	v_and_or_b32 v4, v4, s0, v5
	v_mul_u32_u24_e32 v5, 0x900, v128
	v_add3_u32 v4, 0, v4, v5
	ds_write_b16 v4, v0 offset:34816
	ds_write_b16_d16_hi v4, v0 offset:34960
	v_cvt_pk_bf16_f32 v0, v212, v213
	ds_write_b16 v4, v0 offset:53248
	ds_write_b16_d16_hi v4, v0 offset:53392
	ds_write_b16 v4, v1 offset:35104
	ds_write_b16_d16_hi v4, v1 offset:35248
	v_cvt_pk_bf16_f32 v0, v174, v175
	ds_write_b16 v4, v0 offset:53536
	ds_write_b16_d16_hi v4, v0 offset:53680
	ds_write_b16 v4, v2 offset:35392
	ds_write_b16_d16_hi v4, v2 offset:35536
	v_cvt_pk_bf16_f32 v0, v178, v179
	ds_write_b16 v4, v0 offset:53824
	ds_write_b16_d16_hi v4, v0 offset:53968
	ds_write_b16 v4, v3 offset:35680
	ds_write_b16_d16_hi v4, v3 offset:35824
	v_cvt_pk_bf16_f32 v0, v176, v177
	ds_write_b16 v4, v0 offset:54112
	ds_write_b16_d16_hi v4, v0 offset:54256
	ds_write_b16 v4, v12 offset:35968
	ds_write_b16_d16_hi v4, v12 offset:36112
	v_cvt_pk_bf16_f32 v0, v60, v61
	ds_write_b16 v4, v0 offset:54400
	ds_write_b16_d16_hi v4, v0 offset:54544
	ds_write_b16 v4, v13 offset:36256
	ds_write_b16_d16_hi v4, v13 offset:36400
	v_cvt_pk_bf16_f32 v0, v62, v63
	ds_write_b16 v4, v0 offset:54688
	ds_write_b16_d16_hi v4, v0 offset:54832
	ds_write_b16 v4, v14 offset:36544
	ds_write_b16_d16_hi v4, v14 offset:36688
	v_cvt_pk_bf16_f32 v0, v48, v49
	ds_write_b16 v4, v0 offset:54976
	ds_write_b16_d16_hi v4, v0 offset:55120
	ds_write_b16 v4, v15 offset:36832
	ds_write_b16_d16_hi v4, v15 offset:36976
	v_cvt_pk_bf16_f32 v0, v50, v51
	v_cmp_gt_u32_e64 s[38:39], 64, v186
	ds_write_b16 v4, v0 offset:55264
	ds_write_b16_d16_hi v4, v0 offset:55408
	s_and_saveexec_b64 s[4:5], s[38:39]
	s_cbranch_execz .LBB0_194
	v_lshl_or_b32 v2, s1, 6, v186
	v_readlane_b32 s0, v251, 47
	v_readlane_b32 s1, v251, 48
	s_ashr_i32 s3, s2, 31
	s_mov_b32 s8, 0xc2ce8ed0
	v_mov_b64_e32 v[0:1], s[0:1]
	s_movk_i32 s0, 0xc0
	v_mad_i64_i32 v[0:1], s[0:1], v2, s0, v[0:1]
	v_readlane_b32 s0, v255, 8
	s_mul_i32 s0, s0, 24
	v_readlane_b32 s1, v255, 9
	s_add_i32 s0, s2, s0
	s_ashr_i32 s1, s0, 31
	s_lshl_b64 s[6:7], s[0:1], 2
	v_lshl_add_u64 v[0:1], s[2:3], 2, v[0:1]
	s_add_u32 s2, s70, s6
	s_addc_u32 s3, s71, s7
	global_load_dword v2, v[0:1], off
	global_load_dword v3, v129, s[2:3]
	s_add_i32 s0, s0, 12
	s_ashr_i32 s1, s0, 31
	s_lshl_b64 s[2:3], s[0:1], 2
	s_add_u32 s0, s70, s2
	s_addc_u32 s1, s71, s3
	global_load_dword v4, v129, s[0:1]
	s_add_u32 s0, s68, s6
	s_addc_u32 s1, s69, s7
	s_mov_b32 s7, 0x3fb8aa3b
	s_mov_b32 s9, 0x42b17218
	s_mov_b32 s6, 0xbfb8aa3b
	s_mov_b32 s10, 0xb2a5705f
	s_mov_b32 s11, 0x42ce8ed0
	s_mov_b32 s16, 0xc2b17218
	s_mov_b32 s17, 0x3f2aaaab
	s_mov_b32 s26, 0x3f317218
	s_mov_b32 s27, 0x33800000
	v_cmp_gt_u32_e64 s[42:43], 60, v214
	s_waitcnt vmcnt(1)
	v_add_f32_e32 v3, v2, v3
	global_load_dword v2, v[0:1], off offset:48
	s_waitcnt vmcnt(0)
	v_add_f32_e32 v6, v2, v4
	global_load_dword v2, v129, s[0:1]
	s_add_u32 s0, s68, s2
	s_addc_u32 s1, s69, s3
	v_readlane_b32 s2, v254, 41
	s_waitcnt vmcnt(0)
	v_mul_f32_e32 v4, 0x3fb8aa3b, v2
	v_fma_f32 v5, v2, s7, -v4
	v_rndne_f32_e32 v7, v4
	v_fmac_f32_e32 v5, 0x32a5705f, v2
	v_sub_f32_e32 v4, v4, v7
	v_add_f32_e32 v4, v4, v5
	v_exp_f32_e32 v4, v4
	v_cvt_i32_f32_e32 v5, v7
	v_cmp_ngt_f32_e32 vcc, s8, v2
	v_max_f32_e32 v7, 0, v3
	v_ldexp_f32 v4, v4, v5
	v_cndmask_b32_e32 v4, 0, v4, vcc
	v_cmp_nlt_f32_e32 vcc, s9, v2
	s_nop 1
	v_cndmask_b32_e32 v2, v249, v4, vcc
	v_mul_f32_e64 v4, |v3|, s6
	v_fma_f32 v5, |v3|, s6, -v4
	v_rndne_f32_e32 v8, v4
	v_fma_f32 v5, |v3|, s10, v5
	v_sub_f32_e32 v4, v4, v8
	v_add_f32_e32 v4, v4, v5
	v_exp_f32_e32 v4, v4
	v_cvt_i32_f32_e32 v5, v8
	v_cmp_ngt_f32_e64 vcc, |v3|, s11
	v_ldexp_f32 v4, v4, v5
	s_nop 0
	v_cndmask_b32_e32 v4, 0, v4, vcc
	v_cmp_nlt_f32_e64 vcc, |v3|, s16
	s_nop 1
	v_cndmask_b32_e32 v3, v249, v4, vcc
	v_add_f32_e32 v8, 1.0, v3
	v_add_f32_e32 v4, -1.0, v8
	v_sub_f32_e32 v5, v4, v8
	v_add_f32_e32 v5, 1.0, v5
	v_sub_f32_e32 v4, v3, v4
	v_add_f32_e32 v9, v4, v5
	v_frexp_mant_f32_e32 v4, v8
	v_cmp_gt_f32_e32 vcc, s17, v4
	v_cvt_f64_f32_e32 v[4:5], v8
	v_frexp_exp_i32_f64_e32 v4, v[4:5]
	v_subbrev_co_u32_e32 v4, vcc, 0, v4, vcc
	v_sub_u32_e32 v5, 0, v4
	v_ldexp_f32 v8, v8, v5
	v_ldexp_f32 v5, v9, v5
	v_add_f32_e32 v9, -1.0, v8
	v_add_f32_e32 v10, 1.0, v9
	v_sub_f32_e32 v10, v8, v10
	v_add_f32_e32 v10, v5, v10
	v_add_f32_e32 v11, v9, v10
	v_sub_f32_e32 v9, v9, v11
	v_add_f32_e32 v9, v10, v9
	v_add_f32_e32 v10, 1.0, v8
	v_add_f32_e32 v12, -1.0, v10
	v_sub_f32_e32 v8, v8, v12
	v_add_f32_e32 v5, v5, v8
	v_add_f32_e32 v8, v10, v5
	v_sub_f32_e32 v10, v10, v8
	v_add_f32_e32 v5, v5, v10
	v_rcp_f32_e32 v10, v8
	v_cvt_f32_i32_e32 v4, v4
	v_cmp_neq_f32_e32 vcc, s33, v3
	v_mul_f32_e32 v12, v11, v10
	v_mul_f32_e32 v13, v8, v12
	v_fma_f32 v14, v12, v8, -v13
	v_fmac_f32_e32 v14, v12, v5
	v_add_f32_e32 v15, v13, v14
	v_sub_f32_e32 v16, v11, v15
	v_sub_f32_e32 v11, v11, v16
	v_sub_f32_e32 v13, v15, v13
	v_sub_f32_e32 v11, v11, v15
	v_add_f32_e32 v9, v9, v11
	v_sub_f32_e32 v11, v13, v14
	v_add_f32_e32 v9, v11, v9
	v_add_f32_e32 v11, v16, v9
	v_mul_f32_e32 v13, v10, v11
	v_mul_f32_e32 v14, v8, v13
	v_fma_f32 v8, v13, v8, -v14
	v_fmac_f32_e32 v8, v13, v5
	v_sub_f32_e32 v5, v16, v11
	v_add_f32_e32 v5, v9, v5
	v_add_f32_e32 v9, v14, v8
	v_sub_f32_e32 v15, v11, v9
	v_sub_f32_e32 v11, v11, v15
	v_sub_f32_e32 v14, v9, v14
	v_sub_f32_e32 v9, v11, v9
	v_add_f32_e32 v5, v5, v9
	v_sub_f32_e32 v8, v14, v8
	v_add_f32_e32 v5, v8, v5
	v_add_f32_e32 v8, v12, v13
	v_add_f32_e32 v5, v15, v5
	v_sub_f32_e32 v9, v8, v12
	v_mul_f32_e32 v5, v10, v5
	v_sub_f32_e32 v9, v13, v9
	v_add_f32_e32 v5, v9, v5
	v_mul_f32_e32 v12, 0x3f317218, v4
	v_add_f32_e32 v9, v8, v5
	v_fma_f32 v13, v4, s26, -v12
	v_mul_f32_e32 v10, v9, v9
	v_fmac_f32_e32 v13, 0xb102e308, v4
	v_sub_f32_e32 v4, v9, v8
	v_fmamk_f32 v11, v10, 0x3e9b6dac, v238
	v_sub_f32_e32 v4, v5, v4
	v_add_f32_e32 v5, v12, v13
	v_fmaak_f32 v11, v10, v11, 0x3f2aaada
	v_sub_f32_e32 v8, v5, v12
	v_ldexp_f32 v12, v9, 1
	v_mul_f32_e32 v9, v9, v10
	v_mul_f32_e32 v9, v9, v11
	v_add_f32_e32 v10, v12, v9
	v_sub_f32_e32 v11, v10, v12
	v_ldexp_f32 v4, v4, 1
	v_sub_f32_e32 v9, v9, v11
	v_add_f32_e32 v4, v4, v9
	v_add_f32_e32 v9, v10, v4
	v_sub_f32_e32 v10, v9, v10
	v_sub_f32_e32 v4, v4, v10
	v_add_f32_e32 v10, v5, v9
	v_sub_f32_e32 v11, v10, v5
	v_sub_f32_e32 v12, v10, v11
	v_sub_f32_e32 v8, v13, v8
	v_sub_f32_e32 v5, v5, v12
	v_sub_f32_e32 v9, v9, v11
	v_add_f32_e32 v5, v9, v5
	v_add_f32_e32 v9, v8, v4
	v_sub_f32_e32 v11, v9, v8
	v_sub_f32_e32 v12, v9, v11
	v_sub_f32_e32 v8, v8, v12
	v_sub_f32_e32 v4, v4, v11
	v_add_f32_e32 v5, v9, v5
	v_add_f32_e32 v4, v4, v8
	v_add_f32_e32 v8, v10, v5
	v_sub_f32_e32 v9, v8, v10
	v_sub_f32_e32 v5, v5, v9
	v_add_f32_e32 v4, v4, v5
	global_load_dword v5, v129, s[0:1]
	v_add_f32_e32 v4, v8, v4
	v_cndmask_b32_e32 v4, v249, v4, vcc
	v_cmp_lt_f32_e64 vcc, |v3|, s27
	s_nop 1
	v_cndmask_b32_e32 v3, v4, v3, vcc
	v_add_f32_e32 v3, v7, v3
	v_mul_f32_e64 v4, v3, -v2
	s_waitcnt vmcnt(0)
	v_mul_f32_e32 v7, 0x3fb8aa3b, v5
	v_fma_f32 v8, v5, s7, -v7
	v_rndne_f32_e32 v9, v7
	v_fmac_f32_e32 v8, 0x32a5705f, v5
	v_sub_f32_e32 v7, v7, v9
	v_add_f32_e32 v7, v7, v8
	v_exp_f32_e32 v7, v7
	v_cvt_i32_f32_e32 v8, v9
	v_cmp_ngt_f32_e32 vcc, s8, v5
	v_ldexp_f32 v7, v7, v8
	s_nop 0
	v_cndmask_b32_e32 v7, 0, v7, vcc
	v_cmp_nlt_f32_e32 vcc, s9, v5
	v_max_f32_e32 v8, 0, v6
	s_nop 0
	v_cndmask_b32_e32 v5, v249, v7, vcc
	v_mul_f32_e64 v7, |v6|, s6
	v_fma_f32 v9, |v6|, s6, -v7
	v_rndne_f32_e32 v10, v7
	v_fma_f32 v9, |v6|, s10, v9
	v_sub_f32_e32 v7, v7, v10
	v_add_f32_e32 v7, v7, v9
	v_exp_f32_e32 v7, v7
	v_cvt_i32_f32_e32 v9, v10
	v_cmp_ngt_f32_e64 vcc, |v6|, s11
	v_ldexp_f32 v7, v7, v9
	s_nop 0
	v_cndmask_b32_e32 v7, 0, v7, vcc
	v_cmp_nlt_f32_e64 vcc, |v6|, s16
	s_nop 1
	v_cndmask_b32_e32 v9, v249, v7, vcc
	v_add_f32_e32 v10, 1.0, v9
	v_add_f32_e32 v6, -1.0, v10
	v_sub_f32_e32 v7, v6, v10
	v_add_f32_e32 v7, 1.0, v7
	v_sub_f32_e32 v6, v9, v6
	v_add_f32_e32 v11, v6, v7
	v_frexp_mant_f32_e32 v6, v10
	v_cmp_gt_f32_e32 vcc, s17, v6
	v_cvt_f64_f32_e32 v[6:7], v10
	v_frexp_exp_i32_f64_e32 v6, v[6:7]
	v_subbrev_co_u32_e32 v6, vcc, 0, v6, vcc
	v_sub_u32_e32 v7, 0, v6
	v_ldexp_f32 v10, v10, v7
	v_ldexp_f32 v7, v11, v7
	v_add_f32_e32 v11, -1.0, v10
	v_add_f32_e32 v12, 1.0, v11
	v_sub_f32_e32 v12, v10, v12
	v_add_f32_e32 v12, v7, v12
	v_add_f32_e32 v13, v11, v12
	v_sub_f32_e32 v11, v11, v13
	v_add_f32_e32 v11, v12, v11
	v_add_f32_e32 v12, 1.0, v10
	v_add_f32_e32 v14, -1.0, v12
	v_sub_f32_e32 v10, v10, v14
	v_add_f32_e32 v7, v7, v10
	v_add_f32_e32 v10, v12, v7
	v_sub_f32_e32 v12, v12, v10
	v_add_f32_e32 v7, v7, v12
	v_rcp_f32_e32 v12, v10
	v_cvt_f32_i32_e32 v6, v6
	v_cmp_neq_f32_e32 vcc, s33, v9
	v_mul_f32_e32 v14, v13, v12
	v_mul_f32_e32 v15, v10, v14
	v_fma_f32 v16, v14, v10, -v15
	v_fmac_f32_e32 v16, v14, v7
	v_add_f32_e32 v17, v15, v16
	v_sub_f32_e32 v18, v13, v17
	v_sub_f32_e32 v13, v13, v18
	v_sub_f32_e32 v15, v17, v15
	v_sub_f32_e32 v13, v13, v17
	v_add_f32_e32 v11, v11, v13
	v_sub_f32_e32 v13, v15, v16
	v_add_f32_e32 v11, v13, v11
	v_add_f32_e32 v13, v18, v11
	v_mul_f32_e32 v15, v12, v13
	v_mul_f32_e32 v16, v10, v15
	v_fma_f32 v10, v15, v10, -v16
	v_fmac_f32_e32 v10, v15, v7
	v_sub_f32_e32 v7, v18, v13
	v_add_f32_e32 v7, v11, v7
	v_add_f32_e32 v11, v16, v10
	v_sub_f32_e32 v17, v13, v11
	v_sub_f32_e32 v13, v13, v17
	v_sub_f32_e32 v16, v11, v16
	v_sub_f32_e32 v11, v13, v11
	v_add_f32_e32 v7, v7, v11
	v_sub_f32_e32 v10, v16, v10
	v_add_f32_e32 v7, v10, v7
	v_add_f32_e32 v10, v14, v15
	v_add_f32_e32 v7, v17, v7
	v_sub_f32_e32 v11, v10, v14
	v_mul_f32_e32 v7, v12, v7
	v_sub_f32_e32 v11, v15, v11
	v_add_f32_e32 v7, v11, v7
	v_mul_f32_e32 v14, 0x3f317218, v6
	v_add_f32_e32 v11, v10, v7
	v_fma_f32 v15, v6, s26, -v14
	v_mul_f32_e32 v12, v11, v11
	v_fmac_f32_e32 v15, 0xb102e308, v6
	v_sub_f32_e32 v6, v11, v10
	v_fmamk_f32 v13, v12, 0x3e9b6dac, v238
	v_sub_f32_e32 v6, v7, v6
	v_add_f32_e32 v7, v14, v15
	v_fmaak_f32 v13, v12, v13, 0x3f2aaada
	v_sub_f32_e32 v10, v7, v14
	v_ldexp_f32 v14, v11, 1
	v_mul_f32_e32 v11, v11, v12
	v_mul_f32_e32 v11, v11, v13
	v_add_f32_e32 v12, v14, v11
	v_sub_f32_e32 v13, v12, v14
	v_ldexp_f32 v6, v6, 1
	v_sub_f32_e32 v11, v11, v13
	v_add_f32_e32 v6, v6, v11
	v_add_f32_e32 v11, v12, v6
	v_sub_f32_e32 v12, v11, v12
	v_sub_f32_e32 v6, v6, v12
	v_add_f32_e32 v12, v7, v11
	v_sub_f32_e32 v13, v12, v7
	v_sub_f32_e32 v14, v12, v13
	v_sub_f32_e32 v10, v15, v10
	v_sub_f32_e32 v7, v7, v14
	v_sub_f32_e32 v11, v11, v13
	v_add_f32_e32 v7, v11, v7
	v_add_f32_e32 v11, v10, v6
	v_sub_f32_e32 v13, v11, v10
	v_sub_f32_e32 v14, v11, v13
	v_sub_f32_e32 v10, v10, v14
	v_sub_f32_e32 v6, v6, v13
	v_add_f32_e32 v7, v11, v7
	v_add_f32_e32 v6, v6, v10
	v_add_f32_e32 v10, v12, v7
	v_sub_f32_e32 v11, v10, v12
	v_sub_f32_e32 v7, v7, v11
	v_add_f32_e32 v6, v6, v7
	v_add_f32_e32 v6, v10, v6
	v_cndmask_b32_e32 v6, v249, v6, vcc
	v_cmp_lt_f32_e64 vcc, |v9|, s27
	s_nop 1
	v_cndmask_b32_e32 v6, v6, v9, vcc
	v_add_f32_e32 v6, v8, v6
	global_load_dword v8, v[0:1], off offset:96
	v_mul_f32_e64 v7, v6, -v5
	global_load_dword v0, v[0:1], off offset:144
	s_waitcnt vmcnt(1)
	v_mul_f32_e32 v9, 0xbfb8aa3b, v8
	v_fma_f32 v10, v8, s6, -v9
	v_rndne_f32_e32 v11, v9
	v_fmac_f32_e32 v10, 0xb2a5705f, v8
	v_sub_f32_e32 v9, v9, v11
	v_add_f32_e32 v9, v9, v10
	v_exp_f32_e32 v9, v9
	v_cvt_i32_f32_e32 v10, v11
	v_cmp_nlt_f32_e32 vcc, s11, v8
	s_waitcnt vmcnt(0)
	v_mul_f32_e32 v1, 0xbfb8aa3b, v0
	v_ldexp_f32 v9, v9, v10
	v_cndmask_b32_e32 v9, 0, v9, vcc
	v_cmp_ngt_f32_e32 vcc, s16, v8
	v_rndne_f32_e32 v10, v1
	s_nop 0
	v_cndmask_b32_e32 v8, v249, v9, vcc
	v_fma_f32 v9, v0, s6, -v1
	v_fmac_f32_e32 v9, 0xb2a5705f, v0
	v_sub_f32_e32 v1, v1, v10
	v_add_f32_e32 v1, v1, v9
	v_exp_f32_e32 v1, v1
	v_cvt_i32_f32_e32 v9, v10
	v_cmp_nlt_f32_e32 vcc, s11, v0
	v_add_f32_e32 v8, 1.0, v8
	s_mov_b32 s6, 0x3fb8aa3b
	v_ldexp_f32 v1, v1, v9
	v_cndmask_b32_e32 v1, 0, v1, vcc
	v_cmp_ngt_f32_e32 vcc, s16, v0
	v_add_u32_e32 v9, 4, v124
	s_nop 0
	v_cndmask_b32_e32 v0, v249, v1, vcc
	v_cmp_ne_u32_e32 vcc, 0, v214
	v_add_f32_e32 v0, 1.0, v0
	s_nop 0
	v_subbrev_co_u32_e64 v1, s[40:41], 0, v214, vcc
	v_cmp_eq_u32_e64 s[40:41], 63, v214
	v_lshlrev_b32_e32 v1, 2, v1
	ds_bpermute_b32 v1, v1, v4
	v_cndmask_b32_e64 v9, v9, v242, s[40:41]
	ds_bpermute_b32 v9, v9, v7
	s_waitcnt lgkmcnt(1)
	v_fma_f32 v1, v3, -v2, v1
	v_cndmask_b32_e32 v1, v4, v1, vcc
	s_waitcnt lgkmcnt(0)
	v_fma_f32 v2, v6, -v5, v9
	v_cndmask_b32_e64 v2, v2, v7, s[40:41]
	v_cmp_gt_u32_e64 s[40:41], 2, v214
	v_cmp_gt_u32_e32 vcc, 62, v214
	v_add_u32_e32 v4, 8, v124
	v_cndmask_b32_e64 v3, -2, 0, s[40:41]
	v_add_lshl_u32 v3, v3, v214, 2
	ds_bpermute_b32 v3, v3, v1
	v_cndmask_b32_e32 v4, v124, v4, vcc
	ds_bpermute_b32 v4, v4, v2
	s_waitcnt lgkmcnt(1)
	v_add_f32_e32 v3, v1, v3
	v_cndmask_b32_e64 v1, v3, v1, s[40:41]
	s_waitcnt lgkmcnt(0)
	v_add_f32_e32 v3, v2, v4
	v_cndmask_b32_e32 v2, v2, v3, vcc
	v_cmp_gt_u32_e32 vcc, 4, v214
	v_add_u32_e32 v4, 16, v124
	v_cndmask_b32_e64 v4, v124, v4, s[42:43]
	v_cndmask_b32_e64 v3, -4, 0, vcc
	v_add_lshl_u32 v3, v3, v214, 2
	ds_bpermute_b32 v3, v3, v1
	ds_bpermute_b32 v4, v4, v2
	s_waitcnt lgkmcnt(1)
	v_add_f32_e32 v3, v1, v3
	v_cndmask_b32_e32 v1, v3, v1, vcc
	s_waitcnt lgkmcnt(0)
	v_add_f32_e32 v3, v2, v4
	v_cmp_gt_u32_e32 vcc, 8, v214
	v_cndmask_b32_e64 v2, v2, v3, s[42:43]
	v_cmp_gt_u32_e64 s[42:43], 56, v214
	v_cndmask_b32_e64 v3, -8, 0, vcc
	v_add_lshl_u32 v3, v3, v214, 2
	v_add_u32_e32 v4, 32, v124
	ds_bpermute_b32 v3, v3, v1
	v_cndmask_b32_e64 v4, v124, v4, s[42:43]
	ds_bpermute_b32 v4, v4, v2
	s_waitcnt lgkmcnt(1)
	v_add_f32_e32 v3, v1, v3
	v_cndmask_b32_e32 v1, v3, v1, vcc
	s_waitcnt lgkmcnt(0)
	v_add_f32_e32 v3, v2, v4
	v_cmp_gt_u32_e32 vcc, 16, v214
	v_cndmask_b32_e64 v2, v2, v3, s[42:43]
	v_cmp_gt_u32_e64 s[42:43], 48, v214
	v_cndmask_b32_e64 v3, -16, 0, vcc
	v_add_lshl_u32 v3, v3, v214, 2
	v_add_u32_e32 v4, 64, v124
	ds_bpermute_b32 v3, v3, v1
	v_cndmask_b32_e64 v4, v124, v4, s[42:43]
	ds_bpermute_b32 v4, v4, v2
	s_waitcnt lgkmcnt(1)
	v_add_f32_e32 v3, v1, v3
	v_cndmask_b32_e32 v1, v3, v1, vcc
	s_waitcnt lgkmcnt(0)
	v_add_f32_e32 v3, v2, v4
	v_cndmask_b32_e64 v2, v2, v3, s[42:43]
	v_lshlrev_b32_e32 v3, 2, v216
	v_cmp_gt_u32_e32 vcc, 32, v214
	v_and_b32_e32 v3, 0x7c, v3
	v_add_u32_e32 v4, 0x80, v124
	ds_bpermute_b32 v3, v3, v1
	v_cndmask_b32_e32 v4, v124, v4, vcc
	ds_bpermute_b32 v4, v4, v2
	s_waitcnt lgkmcnt(1)
	v_add_f32_e32 v3, v1, v3
	v_cndmask_b32_e32 v1, v3, v1, vcc
	s_waitcnt lgkmcnt(0)
	v_add_f32_e32 v3, v2, v4
	v_cndmask_b32_e32 v2, v2, v3, vcc
	v_div_scale_f32 v3, s[0:1], v8, v8, 1.0
	v_rcp_f32_e32 v4, v3
	s_nop 0
	v_fma_f32 v5, -v3, v4, 1.0
	v_fmac_f32_e32 v4, v5, v4
	v_div_scale_f32 v5, vcc, 1.0, v8, 1.0
	v_mul_f32_e32 v6, v5, v4
	v_fma_f32 v7, -v3, v6, v5
	v_fmac_f32_e32 v6, v7, v4
	v_fma_f32 v3, -v3, v6, v5
	v_div_fmas_f32 v3, v3, v4, v6
	v_div_scale_f32 v4, s[0:1], v0, v0, 1.0
	v_rcp_f32_e32 v5, v4
	v_div_fixup_f32 v3, v3, v8, 1.0
	v_readlane_b32 s0, v1, 63
	v_readlane_b32 s1, v2, 0
	v_fma_f32 v6, -v4, v5, 1.0
	v_fmac_f32_e32 v5, v6, v5
	v_div_scale_f32 v6, vcc, 1.0, v0, 1.0
	v_mul_f32_e32 v7, v6, v5
	v_fma_f32 v8, -v4, v7, v6
	v_fmac_f32_e32 v7, v8, v5
	v_fma_f32 v4, -v4, v7, v6
	v_div_fmas_f32 v4, v4, v5, v7
	v_div_fixup_f32 v0, v4, v0, 1.0
	v_mul_f32_e32 v4, 0x3fb8aa3b, v1
	v_fma_f32 v5, v1, s7, -v4
	v_rndne_f32_e32 v6, v4
	v_fmac_f32_e32 v5, 0x32a5705f, v1
	v_sub_f32_e32 v4, v4, v6
	v_add_f32_e32 v4, v4, v5
	v_exp_f32_e32 v4, v4
	v_cvt_i32_f32_e32 v5, v6
	v_cmp_ngt_f32_e32 vcc, s8, v1
	v_ldexp_f32 v4, v4, v5
	v_mul_f32_e32 v5, 0x3fb8aa3b, v2
	v_fma_f32 v6, v2, s7, -v5
	v_rndne_f32_e32 v7, v5
	v_fmac_f32_e32 v6, 0x32a5705f, v2
	v_sub_f32_e32 v5, v5, v7
	v_add_f32_e32 v5, v5, v6
	v_exp_f32_e32 v5, v5
	v_cvt_i32_f32_e32 v6, v7
	v_cndmask_b32_e32 v4, 0, v4, vcc
	v_cmp_nlt_f32_e32 vcc, s9, v1
	v_ldexp_f32 v5, v5, v6
	v_lshl_add_u32 v6, v214, 2, s2
	ds_write_b32 v6, v1
	v_sub_f32_e32 v1, s0, v1
	v_mul_f32_e32 v7, 0x3fb8aa3b, v1
	v_fma_f32 v8, v1, s7, -v7
	v_rndne_f32_e32 v9, v7
	v_fmac_f32_e32 v8, 0x32a5705f, v1
	v_sub_f32_e32 v7, v7, v9
	v_add_f32_e32 v7, v7, v8
	v_exp_f32_e32 v7, v7
	v_cvt_i32_f32_e32 v8, v9
	v_cndmask_b32_e32 v4, v249, v4, vcc
	v_cmp_ngt_f32_e32 vcc, s8, v2
	v_lshl_add_u32 v6, v186, 2, s2
	v_ldexp_f32 v7, v7, v8
	v_cndmask_b32_e32 v5, 0, v5, vcc
	v_cmp_nlt_f32_e32 vcc, s9, v2
	ds_write2st64_b32 v6, v2, v3 offset0:1 offset1:2
	ds_write2st64_b32 v6, v0, v4 offset0:3 offset1:4
	v_cndmask_b32_e32 v5, v249, v5, vcc
	v_cmp_ngt_f32_e32 vcc, s8, v1
	v_mul_f32_e32 v0, v0, v5
	ds_write_b32 v6, v0 offset:2304
	v_cndmask_b32_e32 v7, 0, v7, vcc
	v_cmp_nlt_f32_e32 vcc, s9, v1
	s_nop 1
	v_cndmask_b32_e32 v1, v249, v7, vcc
	ds_write2st64_b32 v6, v5, v1 offset0:5 offset1:6
	v_sub_f32_e32 v1, s1, v2
	v_mul_f32_e32 v2, 0x3fb8aa3b, v1
	v_fma_f32 v7, v1, s7, -v2
	v_rndne_f32_e32 v8, v2
	v_fmac_f32_e32 v7, 0x32a5705f, v1
	v_sub_f32_e32 v2, v2, v8
	v_add_f32_e32 v2, v2, v7
	v_exp_f32_e32 v2, v2
	v_cvt_i32_f32_e32 v7, v8
	v_cmp_ngt_f32_e32 vcc, s8, v1
	s_mov_b32 s7, 0xc2ce8ed0
	s_mov_b32 s8, 0x42b17218
	v_ldexp_f32 v2, v2, v7
	v_cndmask_b32_e32 v2, 0, v2, vcc
	v_cmp_nlt_f32_e32 vcc, s9, v1
	s_nop 1
	v_cndmask_b32_e32 v1, v249, v2, vcc
	v_mul_f32_e32 v2, v3, v4
	ds_write2st64_b32 v6, v1, v2 offset0:7 offset1:8
	s_and_b64 exec, exec, s[40:41]
	s_cbranch_execz .LBB0_194
	v_mov_b32_e32 v0, s1
	v_mov_b32_e32 v1, s0
	v_cmp_eq_u32_e32 vcc, 0, v214
	s_ashr_i32 s29, s28, 31
	s_lshl_b64 s[0:1], s[28:29], 3
	v_cndmask_b32_e32 v0, v0, v1, vcc
	v_mul_f32_e32 v1, 0x3fb8aa3b, v0
	v_fma_f32 v2, v0, s6, -v1
	v_rndne_f32_e32 v3, v1
	v_fmac_f32_e32 v2, 0x32a5705f, v0
	v_sub_f32_e32 v1, v1, v3
	v_add_f32_e32 v1, v1, v2
	v_exp_f32_e32 v1, v1
	v_cvt_i32_f32_e32 v2, v3
	v_cmp_ngt_f32_e32 vcc, s7, v0
	v_readlane_b32 s2, v251, 29
	s_add_u32 s0, s2, s0
	v_ldexp_f32 v1, v1, v2
	v_cndmask_b32_e32 v1, 0, v1, vcc
	v_cmp_nlt_f32_e32 vcc, s8, v0
	v_readlane_b32 s2, v251, 30
	s_addc_u32 s1, s2, s1
	v_cndmask_b32_e32 v0, v249, v1, vcc
	global_store_dword v124, v0, s[0:1]
